# v36 + 64-bit moves for accumulator zeroing in the gate|up, FFN1-down and w_in phases (as hipcc already emits for w_out)
# speedup vs baseline: 1.0193x; 1.0062x over previous
;     ...
;         const bool has_next = S.next(ui + 1, nxt);
;         const char* nA = has_next ? (const char*)g.A + (size_t)nxt.pm * tstep : cA; const char* nB = has_next ? (const char*)g.Bt + (size_t)nxt.pn * tstep : cB;
;     ...
; #pragma unroll
;         for (int a = 0; a < 2; ++a)
; #pragma unroll
;             for (int b = 0; b < 2; ++b)
; #pragma unroll
;                 for (int m = 0; m < 4; ++m)
; #pragma unroll
;                     for (int n = 0; n < 2; ++n) acc[a][b][m][n] = (f32x4){0.f, 0.f, 0.f, 0.f};
;         cur = nxt; cA = nA; cB = nB; ++ui;
.LBB0_247:
	s_ashr_i32 s25, s24, 31
	s_lshl_b64 s[34:35], s[24:25], 19
	s_add_u32 s44, s3, s34
	s_addc_u32 s45, s17, s35
	s_and_b64 s[34:35], s[4:5], exec
	s_cselect_b32 s25, s45, s55
	s_cselect_b32 s34, s44, s54
	s_ashr_i32 s21, s20, 31
	s_lshl_b64 s[48:49], s[20:21], 19
	s_add_u32 s48, s18, s48
	s_addc_u32 s49, s19, s49
	s_and_b64 s[72:73], s[4:5], exec
	s_cselect_b32 s21, s49, s53
	s_cselect_b32 s35, s48, s52
	v_lshl_add_u32 v162, s50, 8, v147
	s_add_u32 s50, s54, 0x40080
	s_addc_u32 s51, s55, 0
	v_ashrrev_i32_e32 v163, 31, v162
	s_add_u32 s72, s52, 0x100
	v_mov_b32_e32 v0, 0
	s_addc_u32 s73, s53, 0
	s_mov_b32 s74, -2
	v_mov_b32_e32 v1, v0
	v_mov_b64_e32 v[2:3], v[0:1]
	v_mov_b64_e32 v[8:9], v[0:1]
	v_mov_b64_e32 v[10:11], v[0:1]
	v_mov_b64_e32 v[16:17], v[0:1]
	v_mov_b64_e32 v[18:19], v[0:1]
	v_mov_b64_e32 v[24:25], v[0:1]
	v_mov_b64_e32 v[26:27], v[0:1]
	v_mov_b64_e32 v[32:33], v[0:1]
	v_mov_b64_e32 v[34:35], v[0:1]
	v_mov_b64_e32 v[40:41], v[0:1]
	v_mov_b64_e32 v[42:43], v[0:1]
	v_mov_b64_e32 v[48:49], v[0:1]
	v_mov_b64_e32 v[50:51], v[0:1]
	v_mov_b64_e32 v[56:57], v[0:1]
	v_mov_b64_e32 v[58:59], v[0:1]
	v_mov_b64_e32 v[4:5], v[0:1]
	v_mov_b64_e32 v[6:7], v[0:1]
	v_mov_b64_e32 v[12:13], v[0:1]
	v_mov_b64_e32 v[14:15], v[0:1]
	v_mov_b64_e32 v[20:21], v[0:1]
	v_mov_b64_e32 v[22:23], v[0:1]
	v_mov_b64_e32 v[28:29], v[0:1]
	v_mov_b64_e32 v[30:31], v[0:1]
	v_mov_b64_e32 v[36:37], v[0:1]
	v_mov_b64_e32 v[38:39], v[0:1]
	v_mov_b64_e32 v[44:45], v[0:1]
	v_mov_b64_e32 v[46:47], v[0:1]
	v_mov_b64_e32 v[52:53], v[0:1]
	v_mov_b64_e32 v[54:55], v[0:1]
	v_mov_b64_e32 v[60:61], v[0:1]
	v_mov_b64_e32 v[62:63], v[0:1]
	v_mov_b64_e32 v[64:65], v[0:1]
	v_mov_b64_e32 v[66:67], v[0:1]
	v_mov_b64_e32 v[72:73], v[0:1]
	v_mov_b64_e32 v[74:75], v[0:1]
	v_mov_b64_e32 v[80:81], v[0:1]
	v_mov_b64_e32 v[82:83], v[0:1]
	v_mov_b64_e32 v[88:89], v[0:1]
	v_mov_b64_e32 v[90:91], v[0:1]
	v_mov_b64_e32 v[96:97], v[0:1]
	v_mov_b64_e32 v[98:99], v[0:1]
	v_mov_b64_e32 v[104:105], v[0:1]
	v_mov_b64_e32 v[106:107], v[0:1]
	v_mov_b64_e32 v[112:113], v[0:1]
	v_mov_b64_e32 v[114:115], v[0:1]
	v_mov_b64_e32 v[120:121], v[0:1]
	v_mov_b64_e32 v[122:123], v[0:1]
	v_mov_b64_e32 v[68:69], v[0:1]
	v_mov_b64_e32 v[70:71], v[0:1]
	v_mov_b64_e32 v[76:77], v[0:1]
	v_mov_b64_e32 v[78:79], v[0:1]
	v_mov_b64_e32 v[84:85], v[0:1]
	v_mov_b64_e32 v[86:87], v[0:1]
	v_mov_b64_e32 v[92:93], v[0:1]
	v_mov_b64_e32 v[94:95], v[0:1]
	v_mov_b64_e32 v[100:101], v[0:1]
	v_mov_b64_e32 v[102:103], v[0:1]
	v_mov_b64_e32 v[108:109], v[0:1]
	v_mov_b64_e32 v[110:111], v[0:1]
	v_mov_b64_e32 v[116:117], v[0:1]
	v_mov_b64_e32 v[118:119], v[0:1]
	v_mov_b64_e32 v[124:125], v[0:1]
	v_mov_b64_e32 v[126:127], v[0:1]
	v_lshl_add_u64 v[164:165], v[162:163], 2, s[8:9]
	s_branch .LBB0_249

;     ...
; #pragma unroll
;         for (int a = 0; a < 2; ++a)
; #pragma unroll
;             for (int b = 0; b < 2; ++b)
; #pragma unroll
;                 for (int m = 0; m < 4; ++m)
; #pragma unroll
;                     for (int n = 0; n < 2; ++n) acc[a][b][m][n] = (f32x4){0.f, 0.f, 0.f, 0.f};
;         cur = nxt; cA = nA; cB = nB; ++ui;
.LBB0_334:
	s_add_u32 s50, s50, 0x160080
	s_addc_u32 s51, s51, 0
	s_add_u32 s34, s52, 0x100
	v_mov_b32_e32 v0, 0
	s_addc_u32 s35, s53, 0
	s_mov_b32 s72, -2
	s_waitcnt lgkmcnt(0)
	v_mov_b32_e32 v1, v0
	v_mov_b64_e32 v[2:3], v[0:1]
	v_mov_b64_e32 v[4:5], v[0:1]
	v_mov_b64_e32 v[6:7], v[0:1]
	v_mov_b64_e32 v[16:17], v[0:1]
	v_mov_b64_e32 v[18:19], v[0:1]
	v_mov_b64_e32 v[20:21], v[0:1]
	v_mov_b64_e32 v[22:23], v[0:1]
	v_mov_b64_e32 v[32:33], v[0:1]
	v_mov_b64_e32 v[34:35], v[0:1]
	v_mov_b64_e32 v[36:37], v[0:1]
	v_mov_b64_e32 v[38:39], v[0:1]
	v_mov_b64_e32 v[48:49], v[0:1]
	v_mov_b64_e32 v[50:51], v[0:1]
	v_mov_b64_e32 v[52:53], v[0:1]
	v_mov_b64_e32 v[54:55], v[0:1]
	v_mov_b64_e32 v[8:9], v[0:1]
	v_mov_b64_e32 v[10:11], v[0:1]
	v_mov_b64_e32 v[12:13], v[0:1]
	v_mov_b64_e32 v[14:15], v[0:1]
	v_mov_b64_e32 v[24:25], v[0:1]
	v_mov_b64_e32 v[26:27], v[0:1]
	v_mov_b64_e32 v[28:29], v[0:1]
	v_mov_b64_e32 v[30:31], v[0:1]
	v_mov_b64_e32 v[40:41], v[0:1]
	v_mov_b64_e32 v[42:43], v[0:1]
	v_mov_b64_e32 v[44:45], v[0:1]
	v_mov_b64_e32 v[46:47], v[0:1]
	v_mov_b64_e32 v[56:57], v[0:1]
	v_mov_b64_e32 v[58:59], v[0:1]
	v_mov_b64_e32 v[60:61], v[0:1]
	v_mov_b64_e32 v[62:63], v[0:1]
	v_mov_b64_e32 v[64:65], v[0:1]
	v_mov_b64_e32 v[66:67], v[0:1]
	v_mov_b64_e32 v[68:69], v[0:1]
	v_mov_b64_e32 v[70:71], v[0:1]
	v_mov_b64_e32 v[80:81], v[0:1]
	v_mov_b64_e32 v[82:83], v[0:1]
	v_mov_b64_e32 v[84:85], v[0:1]
	v_mov_b64_e32 v[86:87], v[0:1]
	v_mov_b64_e32 v[96:97], v[0:1]
	v_mov_b64_e32 v[98:99], v[0:1]
	v_mov_b64_e32 v[100:101], v[0:1]
	v_mov_b64_e32 v[102:103], v[0:1]
	v_mov_b64_e32 v[112:113], v[0:1]
	v_mov_b64_e32 v[114:115], v[0:1]
	v_mov_b64_e32 v[116:117], v[0:1]
	v_mov_b64_e32 v[118:119], v[0:1]
	v_mov_b64_e32 v[72:73], v[0:1]
	v_mov_b64_e32 v[74:75], v[0:1]
	v_mov_b64_e32 v[76:77], v[0:1]
	v_mov_b64_e32 v[78:79], v[0:1]
	v_mov_b64_e32 v[88:89], v[0:1]
	v_mov_b64_e32 v[90:91], v[0:1]
	v_mov_b64_e32 v[92:93], v[0:1]
	v_mov_b64_e32 v[94:95], v[0:1]
	v_mov_b64_e32 v[104:105], v[0:1]
	v_mov_b64_e32 v[106:107], v[0:1]
	v_mov_b64_e32 v[108:109], v[0:1]
	v_mov_b64_e32 v[110:111], v[0:1]
	v_mov_b64_e32 v[120:121], v[0:1]
	v_mov_b64_e32 v[122:123], v[0:1]
	v_mov_b64_e32 v[124:125], v[0:1]
	v_mov_b64_e32 v[126:127], v[0:1]

;     ...
;         const bool has_next = S.next(ui + 1, nxt);
;         const char* nA = has_next ? (const char*)g.A + (size_t)nxt.pm * tstep : cA; const char* nB = has_next ? (const char*)g.Bt + (size_t)nxt.pn * tstep : cB;
;     ...
; #pragma unroll
;         for (int a = 0; a < 2; ++a)
; #pragma unroll
;             for (int b = 0; b < 2; ++b)
; #pragma unroll
;                 for (int m = 0; m < 4; ++m)
; #pragma unroll
;                     for (int n = 0; n < 2; ++n) acc[a][b][m][n] = (f32x4){0.f, 0.f, 0.f, 0.f};
;         cur = nxt; cA = nA; cB = nB; ++ui;
.LBB0_431:
	s_ashr_i32 s63, s62, 31
	s_lshl_b64 s[18:19], s[62:63], 20
	s_add_u32 s64, s16, s18
	s_addc_u32 s65, s17, s19
	s_and_b64 s[18:19], s[6:7], exec
	s_cselect_b32 s18, s65, s71
	s_cselect_b32 s19, s64, s70
	s_ashr_i32 s61, s60, 31
	s_lshl_b64 s[34:35], s[60:61], 20
	s_add_u32 s66, s80, s34
	s_addc_u32 s67, s81, s35
	s_and_b64 s[34:35], s[6:7], exec
	s_cselect_b32 s34, s67, s73
	s_cselect_b32 s35, s66, s72
	s_add_u32 s70, s70, 0x80080
	v_lshl_add_u32 v186, s10, 8, v204
	s_addc_u32 s71, s71, 0
	v_ashrrev_i32_e32 v187, 31, v186
	s_add_u32 s10, s72, 0x100
	v_mov_b32_e32 v0, 0
	v_lshl_add_u64 v[128:129], v[186:187], 2, s[8:9]
	s_addc_u32 s61, s73, 0
	s_mov_b32 s63, -2
	v_mov_b32_e32 v1, v0
	v_mov_b64_e32 v[2:3], v[0:1]
	v_mov_b64_e32 v[4:5], v[0:1]
	v_mov_b64_e32 v[6:7], v[0:1]
	v_mov_b64_e32 v[16:17], v[0:1]
	v_mov_b64_e32 v[18:19], v[0:1]
	v_mov_b64_e32 v[20:21], v[0:1]
	v_mov_b64_e32 v[22:23], v[0:1]
	v_mov_b64_e32 v[32:33], v[0:1]
	v_mov_b64_e32 v[34:35], v[0:1]
	v_mov_b64_e32 v[36:37], v[0:1]
	v_mov_b64_e32 v[38:39], v[0:1]
	v_mov_b64_e32 v[48:49], v[0:1]
	v_mov_b64_e32 v[50:51], v[0:1]
	v_mov_b64_e32 v[52:53], v[0:1]
	v_mov_b64_e32 v[54:55], v[0:1]
	v_mov_b64_e32 v[8:9], v[0:1]
	v_mov_b64_e32 v[10:11], v[0:1]
	v_mov_b64_e32 v[12:13], v[0:1]
	v_mov_b64_e32 v[14:15], v[0:1]
	v_mov_b64_e32 v[24:25], v[0:1]
	v_mov_b64_e32 v[26:27], v[0:1]
	v_mov_b64_e32 v[28:29], v[0:1]
	v_mov_b64_e32 v[30:31], v[0:1]
	v_mov_b64_e32 v[40:41], v[0:1]
	v_mov_b64_e32 v[42:43], v[0:1]
	v_mov_b64_e32 v[44:45], v[0:1]
	v_mov_b64_e32 v[46:47], v[0:1]
	v_mov_b64_e32 v[56:57], v[0:1]
	v_mov_b64_e32 v[58:59], v[0:1]
	v_mov_b64_e32 v[60:61], v[0:1]
	v_mov_b64_e32 v[62:63], v[0:1]
	v_mov_b64_e32 v[64:65], v[0:1]
	v_mov_b64_e32 v[66:67], v[0:1]
	v_mov_b64_e32 v[68:69], v[0:1]
	v_mov_b64_e32 v[70:71], v[0:1]
	v_mov_b64_e32 v[80:81], v[0:1]
	v_mov_b64_e32 v[82:83], v[0:1]
	v_mov_b64_e32 v[84:85], v[0:1]
	v_mov_b64_e32 v[86:87], v[0:1]
	v_mov_b64_e32 v[96:97], v[0:1]
	v_mov_b64_e32 v[98:99], v[0:1]
	v_mov_b64_e32 v[100:101], v[0:1]
	v_mov_b64_e32 v[102:103], v[0:1]
	v_mov_b64_e32 v[112:113], v[0:1]
	v_mov_b64_e32 v[114:115], v[0:1]
	v_mov_b64_e32 v[116:117], v[0:1]
	v_mov_b64_e32 v[118:119], v[0:1]
	v_mov_b64_e32 v[72:73], v[0:1]
	v_mov_b64_e32 v[74:75], v[0:1]
	v_mov_b64_e32 v[76:77], v[0:1]
	v_mov_b64_e32 v[78:79], v[0:1]
	v_mov_b64_e32 v[88:89], v[0:1]
	v_mov_b64_e32 v[90:91], v[0:1]
	v_mov_b64_e32 v[92:93], v[0:1]
	v_mov_b64_e32 v[94:95], v[0:1]
	v_mov_b64_e32 v[104:105], v[0:1]
	v_mov_b64_e32 v[106:107], v[0:1]
	v_mov_b64_e32 v[108:109], v[0:1]
	v_mov_b64_e32 v[110:111], v[0:1]
	v_mov_b64_e32 v[120:121], v[0:1]
	v_mov_b64_e32 v[122:123], v[0:1]
	v_mov_b64_e32 v[124:125], v[0:1]
	v_mov_b64_e32 v[126:127], v[0:1]
	s_branch .LBB0_433

;     ...
;         const bool has_next = S.next(ui + 1, nxt);
;         const char* nA = has_next ? (const char*)g.A + (size_t)nxt.pm * tstep : cA; const char* nB = has_next ? (const char*)g.Bt + (size_t)nxt.pn * tstep : cB;
;     ...
; #pragma unroll
;         for (int a = 0; a < 2; ++a)
; #pragma unroll
;             for (int b = 0; b < 2; ++b)
; #pragma unroll
;                 for (int m = 0; m < 4; ++m)
; #pragma unroll
;                     for (int n = 0; n < 2; ++n) acc[a][b][m][n] = (f32x4){0.f, 0.f, 0.f, 0.f};
;         cur = nxt; cA = nA; cB = nB; ++ui;
.LBB0_850:
	s_ashr_i32 s37, s36, 31
	s_lshl_b64 s[34:35], s[36:37], 19
	s_add_u32 s38, s3, s34
	s_addc_u32 s39, s18, s35
	s_and_b64 s[34:35], s[4:5], exec
	s_cselect_b32 s34, s39, s47
	s_cselect_b32 s35, s38, s46
	s_ashr_i32 s25, s24, 31
	s_lshl_b64 s[40:41], s[24:25], 19
	s_add_u32 s40, s19, s40
	s_addc_u32 s41, s21, s41
	s_and_b64 s[66:67], s[4:5], exec
	s_cselect_b32 s25, s41, s45
	s_cselect_b32 s37, s40, s44
	v_lshl_add_u32 v162, s42, 8, v147
	s_add_u32 s42, s46, 0x40080
	s_addc_u32 s43, s47, 0
	v_ashrrev_i32_e32 v163, 31, v162
	s_add_u32 s65, s44, 0x100
	v_mov_b32_e32 v0, 0
	v_lshl_add_u64 v[164:165], v[162:163], 2, s[0:1]
	s_addc_u32 s66, s45, 0
	s_mov_b32 s67, -2
	v_mov_b32_e32 v1, v0
	v_mov_b64_e32 v[2:3], v[0:1]
	v_mov_b64_e32 v[8:9], v[0:1]
	v_mov_b64_e32 v[10:11], v[0:1]
	v_mov_b64_e32 v[16:17], v[0:1]
	v_mov_b64_e32 v[18:19], v[0:1]
	v_mov_b64_e32 v[24:25], v[0:1]
	v_mov_b64_e32 v[26:27], v[0:1]
	v_mov_b64_e32 v[32:33], v[0:1]
	v_mov_b64_e32 v[34:35], v[0:1]
	v_mov_b64_e32 v[40:41], v[0:1]
	v_mov_b64_e32 v[42:43], v[0:1]
	v_mov_b64_e32 v[48:49], v[0:1]
	v_mov_b64_e32 v[50:51], v[0:1]
	v_mov_b64_e32 v[56:57], v[0:1]
	v_mov_b64_e32 v[58:59], v[0:1]
	v_mov_b64_e32 v[4:5], v[0:1]
	v_mov_b64_e32 v[6:7], v[0:1]
	v_mov_b64_e32 v[12:13], v[0:1]
	v_mov_b64_e32 v[14:15], v[0:1]
	v_mov_b64_e32 v[20:21], v[0:1]
	v_mov_b64_e32 v[22:23], v[0:1]
	v_mov_b64_e32 v[28:29], v[0:1]
	v_mov_b64_e32 v[30:31], v[0:1]
	v_mov_b64_e32 v[36:37], v[0:1]
	v_mov_b64_e32 v[38:39], v[0:1]
	v_mov_b64_e32 v[44:45], v[0:1]
	v_mov_b64_e32 v[46:47], v[0:1]
	v_mov_b64_e32 v[52:53], v[0:1]
	v_mov_b64_e32 v[54:55], v[0:1]
	v_mov_b64_e32 v[60:61], v[0:1]
	v_mov_b64_e32 v[62:63], v[0:1]
	v_mov_b64_e32 v[64:65], v[0:1]
	v_mov_b64_e32 v[66:67], v[0:1]
	v_mov_b64_e32 v[72:73], v[0:1]
	v_mov_b64_e32 v[74:75], v[0:1]
	v_mov_b64_e32 v[80:81], v[0:1]
	v_mov_b64_e32 v[82:83], v[0:1]
	v_mov_b64_e32 v[88:89], v[0:1]
	v_mov_b64_e32 v[90:91], v[0:1]
	v_mov_b64_e32 v[96:97], v[0:1]
	v_mov_b64_e32 v[98:99], v[0:1]
	v_mov_b64_e32 v[104:105], v[0:1]
	v_mov_b64_e32 v[106:107], v[0:1]
	v_mov_b64_e32 v[112:113], v[0:1]
	v_mov_b64_e32 v[114:115], v[0:1]
	v_mov_b64_e32 v[116:117], v[0:1]
	v_mov_b64_e32 v[118:119], v[0:1]
	v_mov_b64_e32 v[68:69], v[0:1]
	v_mov_b64_e32 v[70:71], v[0:1]
	v_mov_b64_e32 v[76:77], v[0:1]
	v_mov_b64_e32 v[78:79], v[0:1]
	v_mov_b64_e32 v[84:85], v[0:1]
	v_mov_b64_e32 v[86:87], v[0:1]
	v_mov_b64_e32 v[92:93], v[0:1]
	v_mov_b64_e32 v[94:95], v[0:1]
	v_mov_b64_e32 v[100:101], v[0:1]
	v_mov_b64_e32 v[102:103], v[0:1]
	v_mov_b64_e32 v[108:109], v[0:1]
	v_mov_b64_e32 v[110:111], v[0:1]
	v_mov_b64_e32 v[120:121], v[0:1]
	v_mov_b64_e32 v[122:123], v[0:1]
	v_mov_b64_e32 v[124:125], v[0:1]
	v_mov_b64_e32 v[126:127], v[0:1]
	s_branch .LBB0_852
